# combine phase: the second map's split-KV partial loads of the sample rows are issued together instead of one dependent round trip each
# speedup vs baseline: 1.0137x; 1.0137x over previous
.LBB0_2128:
	s_or_b64 exec, exec, vcc
	s_waitcnt vmcnt(32)
	v_pk_fma_f32 v[12:13], v[16:17], s[92:93], 0 op_sel_hi:[1,0,0]
	v_add_f32_e32 v14, v89, v90
	s_waitcnt vmcnt(31)
	v_pk_fma_f32 v[12:13], v[20:21], s[90:91], v[12:13] op_sel_hi:[1,0,1]
	s_add_i32 s91, s91, s36
	s_waitcnt vmcnt(30)
	v_pk_fma_f32 v[12:13], v[18:19], s[88:89], v[12:13] op_sel_hi:[1,0,1]
	s_waitcnt vmcnt(29)
	v_pk_fma_f32 v[12:13], v[22:23], s[86:87], v[12:13] op_sel_hi:[1,0,1]
	s_waitcnt vmcnt(28)
	v_pk_fma_f32 v[12:13], v[30:31], s[84:85], v[12:13] op_sel_hi:[1,0,1]
	s_waitcnt vmcnt(27)
	v_pk_fma_f32 v[12:13], v[26:27], s[82:83], v[12:13] op_sel_hi:[1,0,1]
	s_waitcnt vmcnt(26)
	v_pk_fma_f32 v[12:13], v[24:25], s[80:81], v[12:13] op_sel_hi:[1,0,1]
	s_waitcnt vmcnt(25)
	v_pk_fma_f32 v[12:13], v[28:29], s[78:79], v[12:13] op_sel_hi:[1,0,1]
	s_waitcnt vmcnt(24)
	v_pk_fma_f32 v[12:13], v[38:39], s[76:77], v[12:13] op_sel_hi:[1,0,1]
	s_waitcnt vmcnt(23)
	v_pk_fma_f32 v[12:13], v[34:35], s[22:23], v[12:13] op_sel_hi:[1,0,1]
	v_div_scale_f32 v15, s[22:23], v14, v14, 1.0
	v_rcp_f32_e32 v16, v15
	s_lshl_b64 s[22:23], s[10:11], 9
	s_waitcnt vmcnt(22)
	v_pk_fma_f32 v[12:13], v[36:37], s[24:25], v[12:13] op_sel_hi:[1,0,1]
	v_fma_f32 v17, -v15, v16, 1.0
	v_fmac_f32_e32 v16, v17, v16
	v_div_scale_f32 v17, vcc, 1.0, v14, 1.0
	v_mul_f32_e32 v18, v17, v16
	v_fma_f32 v19, -v15, v18, v17
	v_fmac_f32_e32 v18, v19, v16
	v_fma_f32 v15, -v15, v18, v17
	v_div_fmas_f32 v15, v15, v16, v18
	v_div_fixup_f32 v14, v15, v14, 1.0
	s_waitcnt vmcnt(0)
	ds_swizzle_b32 v15, v88 offset:swizzle(SWAP,1)
	v_max_f32_e32 v16, v88, v88
	v_pk_fma_f32 v[12:13], v[40:41], s[26:27], v[12:13] op_sel_hi:[1,0,1]
	s_waitcnt lgkmcnt(0)
	v_max_f32_e32 v15, v15, v15
	v_max_f32_e32 v15, v16, v15
	ds_swizzle_b32 v16, v15 offset:swizzle(SWAP,2)
	v_pk_fma_f32 v[12:13], v[42:43], s[28:29], v[12:13] op_sel_hi:[1,0,1]
	s_waitcnt lgkmcnt(0)
	v_max_f32_e32 v16, v16, v16
	v_max_f32_e32 v15, v15, v16
	ds_swizzle_b32 v16, v15 offset:swizzle(SWAP,4)
	v_pk_fma_f32 v[12:13], v[44:45], s[30:31], v[12:13] op_sel_hi:[1,0,1]
	s_waitcnt lgkmcnt(0)
	v_max_f32_e32 v16, v16, v16
	v_max_f32_e32 v15, v15, v16
	ds_swizzle_b32 v16, v15 offset:swizzle(SWAP,8)
	v_pk_fma_f32 v[12:13], v[46:47], s[34:35], v[12:13] op_sel_hi:[1,0,1]
	s_waitcnt lgkmcnt(0)
	v_max_f32_e32 v16, v16, v16
	v_max_f32_e32 v15, v15, v16
	ds_swizzle_b32 v16, v15 offset:swizzle(SWAP,16)
	v_pk_fma_f32 v[12:13], v[48:49], s[46:47], v[12:13] op_sel_hi:[1,0,1]
	s_waitcnt lgkmcnt(0)
	v_max_f32_e32 v16, v16, v16
	v_max_f32_e32 v15, v15, v16
	v_mov_b32_e32 v16, v15
	s_nop 1
	v_permlane32_swap_b32_e32 v15, v16
	v_max_f32_e32 v16, v16, v16
	v_max_f32_e32 v15, v15, v15
	v_max_f32_e32 v15, v15, v16
	v_sub_f32_e32 v15, v88, v15
	v_cmp_gt_f32_e32 vcc, s1, v15
	v_pk_fma_f32 v[12:13], v[50:51], s[50:51], v[12:13] op_sel_hi:[1,0,1]
	s_nop 0
	v_cndmask_b32_e32 v16, 0, v7, vcc
	v_add_f32_e32 v15, v15, v16
	v_exp_f32_e32 v15, v15
	v_cndmask_b32_e32 v16, 0, v84, vcc
	v_pk_fma_f32 v[12:13], v[52:53], s[52:53], v[12:13] op_sel_hi:[1,0,1]
	v_ldexp_f32 v15, v15, v16
	v_cndmask_b32_e64 v19, 0, v15, s[2:3]
	v_mul_f32_e32 v15, v87, v19
	ds_swizzle_b32 v15, v15 offset:swizzle(SWAP,1)
	v_readlane_b32 s10, v19, 0
	v_pk_fma_f32 v[12:13], v[54:55], s[54:55], v[12:13] op_sel_hi:[1,0,1]
	s_waitcnt lgkmcnt(0)
	v_fmac_f32_e32 v15, v87, v19
	ds_swizzle_b32 v16, v15 offset:swizzle(SWAP,2)
	v_pk_fma_f32 v[12:13], v[58:59], s[56:57], v[12:13] op_sel_hi:[1,0,1]
	s_waitcnt lgkmcnt(0)
	v_add_f32_e32 v15, v15, v16
	ds_swizzle_b32 v16, v15 offset:swizzle(SWAP,4)
	v_pk_fma_f32 v[12:13], v[60:61], s[58:59], v[12:13] op_sel_hi:[1,0,1]
	s_waitcnt lgkmcnt(0)
	v_add_f32_e32 v15, v15, v16
	ds_swizzle_b32 v16, v15 offset:swizzle(SWAP,8)
	v_pk_fma_f32 v[12:13], v[62:63], s[60:61], v[12:13] op_sel_hi:[1,0,1]
	s_waitcnt lgkmcnt(0)
	v_add_f32_e32 v15, v15, v16
	ds_swizzle_b32 v16, v15 offset:swizzle(SWAP,16)
	v_pk_fma_f32 v[12:13], v[64:65], s[62:63], v[12:13] op_sel_hi:[1,0,1]
	s_waitcnt lgkmcnt(0)
	v_add_f32_e32 v15, v15, v16
	v_lshl_add_u64 v[16:17], v[4:5], 0, s[22:23]
	v_lshl_add_u64 v[16:17], v[16:17], 0, s[20:21]
	v_add_co_u32_e32 v22, vcc, s25, v16
	global_load_dwordx2 v[20:21], v[16:17], off
	s_nop 0
	v_addc_co_u32_e32 v23, vcc, 0, v17, vcc
	global_load_dwordx2 v[22:23], v[22:23], off
	s_mov_b32 s20, 0x3e000
	v_mov_b32_e32 v18, v15
	s_nop 1
	v_permlane32_swap_b32_e32 v15, v18
	v_add_f32_e32 v15, v15, v18
	v_pk_fma_f32 v[12:13], v[66:67], s[64:65], v[12:13] op_sel_hi:[1,0,1]
	s_waitcnt vmcnt(1)
	v_pk_fma_f32 v[20:21], v[20:21], s[10:11], 0 op_sel_hi:[1,0,0]
	v_readlane_b32 s10, v19, 1
	v_pk_fma_f32 v[12:13], v[68:69], s[66:67], v[12:13] op_sel_hi:[1,0,1]
	s_waitcnt vmcnt(0)
	v_pk_fma_f32 v[20:21], v[22:23], s[10:11], v[20:21] op_sel_hi:[1,0,1]
	v_add_co_u32_e32 v120, vcc, s27, v16
	s_nop 1
	v_addc_co_u32_e32 v121, vcc, 0, v17, vcc
	global_load_dwordx2 v[120:121], v[120:121], off
	v_pk_fma_f32 v[12:13], v[70:71], s[68:69], v[12:13] op_sel_hi:[1,0,1]
	v_add_co_u32_e32 v122, vcc, s29, v16
	s_nop 1
	v_addc_co_u32_e32 v123, vcc, 0, v17, vcc
	global_load_dwordx2 v[122:123], v[122:123], off
	v_pk_fma_f32 v[12:13], v[72:73], s[70:71], v[12:13] op_sel_hi:[1,0,1]
	v_add_co_u32_e32 v124, vcc, s31, v16
	s_nop 1
	v_addc_co_u32_e32 v125, vcc, 0, v17, vcc
	global_load_dwordx2 v[124:125], v[124:125], off
	v_pk_fma_f32 v[12:13], v[74:75], s[72:73], v[12:13] op_sel_hi:[1,0,1]
	v_add_co_u32_e32 v126, vcc, s35, v16
	s_nop 1
	v_addc_co_u32_e32 v127, vcc, 0, v17, vcc
	global_load_dwordx2 v[126:127], v[126:127], off
	v_pk_fma_f32 v[12:13], v[76:77], s[74:75], v[12:13] op_sel_hi:[1,0,1]
	v_add_co_u32_e32 v128, vcc, s37, v16
	s_nop 1
	v_addc_co_u32_e32 v129, vcc, 0, v17, vcc
	global_load_dwordx2 v[128:129], v[128:129], off
	v_pk_fma_f32 v[12:13], v[78:79], s[94:95], v[12:13] op_sel_hi:[1,0,1]
	v_add_co_u32_e32 v130, vcc, s39, v16
	s_nop 1
	v_addc_co_u32_e32 v131, vcc, 0, v17, vcc
	global_load_dwordx2 v[130:131], v[130:131], off
	v_pk_fma_f32 v[12:13], v[80:81], s[96:97], v[12:13] op_sel_hi:[1,0,1]
	v_add_co_u32_e32 v132, vcc, s41, v16
	s_nop 1
	v_addc_co_u32_e32 v133, vcc, 0, v17, vcc
	global_load_dwordx2 v[132:133], v[132:133], off
	v_pk_fma_f32 v[12:13], v[82:83], s[44:45], v[12:13] op_sel_hi:[1,0,1]
	v_add_co_u32_e32 v134, vcc, s45, v16
	s_nop 1
	v_addc_co_u32_e32 v135, vcc, 0, v17, vcc
	global_load_dwordx2 v[134:135], v[134:135], off
	v_pk_fma_f32 v[12:13], v[32:33], s[40:41], v[12:13] op_sel_hi:[1,0,1]
	v_add_co_u32_e32 v136, vcc, s47, v16
	s_nop 1
	v_addc_co_u32_e32 v137, vcc, 0, v17, vcc
	global_load_dwordx2 v[136:137], v[136:137], off
	v_add_co_u32_e32 v138, vcc, s48, v16
	s_nop 1
	v_addc_co_u32_e32 v139, vcc, 0, v17, vcc
	global_load_dwordx2 v[138:139], v[138:139], off
	v_add_co_u32_e32 v140, vcc, s49, v16
	s_nop 1
	v_addc_co_u32_e32 v141, vcc, 0, v17, vcc
	global_load_dwordx2 v[140:141], v[140:141], off
	v_add_co_u32_e32 v142, vcc, s51, v16
	s_nop 1
	v_addc_co_u32_e32 v143, vcc, 0, v17, vcc
	global_load_dwordx2 v[142:143], v[142:143], off
	v_add_co_u32_e32 v144, vcc, s53, v16
	s_nop 1
	v_addc_co_u32_e32 v145, vcc, 0, v17, vcc
	global_load_dwordx2 v[144:145], v[144:145], off
	v_add_co_u32_e32 v146, vcc, s55, v16
	s_nop 1
	v_addc_co_u32_e32 v147, vcc, 0, v17, vcc
	global_load_dwordx2 v[146:147], v[146:147], off
	v_add_co_u32_e32 v148, vcc, s57, v16
	s_nop 1
	v_addc_co_u32_e32 v149, vcc, 0, v17, vcc
	global_load_dwordx2 v[148:149], v[148:149], off
	v_add_co_u32_e32 v150, vcc, s59, v16
	s_nop 1
	v_addc_co_u32_e32 v151, vcc, 0, v17, vcc
	global_load_dwordx2 v[150:151], v[150:151], off
	v_add_co_u32_e32 v152, vcc, s61, v16
	s_nop 1
	v_addc_co_u32_e32 v153, vcc, 0, v17, vcc
	global_load_dwordx2 v[152:153], v[152:153], off
	v_add_co_u32_e32 v154, vcc, s63, v16
	s_nop 1
	v_addc_co_u32_e32 v155, vcc, 0, v17, vcc
	global_load_dwordx2 v[154:155], v[154:155], off
	v_add_co_u32_e32 v156, vcc, s65, v16
	s_nop 1
	v_addc_co_u32_e32 v157, vcc, 0, v17, vcc
	global_load_dwordx2 v[156:157], v[156:157], off
	v_add_co_u32_e32 v158, vcc, s67, v16
	s_nop 1
	v_addc_co_u32_e32 v159, vcc, 0, v17, vcc
	global_load_dwordx2 v[158:159], v[158:159], off
	v_add_co_u32_e32 v160, vcc, s69, v16
	s_nop 1
	v_addc_co_u32_e32 v161, vcc, 0, v17, vcc
	global_load_dwordx2 v[160:161], v[160:161], off
	v_add_co_u32_e32 v162, vcc, s71, v16
	s_nop 1
	v_addc_co_u32_e32 v163, vcc, 0, v17, vcc
	global_load_dwordx2 v[162:163], v[162:163], off
	v_add_co_u32_e32 v164, vcc, s75, v16
	s_nop 1
	v_addc_co_u32_e32 v165, vcc, 0, v17, vcc
	global_load_dwordx2 v[164:165], v[164:165], off
	v_add_co_u32_e32 v166, vcc, s77, v16
	s_nop 1
	v_addc_co_u32_e32 v167, vcc, 0, v17, vcc
	global_load_dwordx2 v[166:167], v[166:167], off
	v_add_co_u32_e32 v168, vcc, s79, v16
	s_nop 1
	v_addc_co_u32_e32 v169, vcc, 0, v17, vcc
	global_load_dwordx2 v[168:169], v[168:169], off
	v_add_co_u32_e32 v170, vcc, s81, v16
	s_nop 1
	v_addc_co_u32_e32 v171, vcc, 0, v17, vcc
	global_load_dwordx2 v[170:171], v[170:171], off
	v_add_co_u32_e32 v172, vcc, s83, v16
	s_nop 1
	v_addc_co_u32_e32 v173, vcc, 0, v17, vcc
	global_load_dwordx2 v[172:173], v[172:173], off
	v_add_co_u32_e32 v174, vcc, s85, v16
	s_nop 1
	v_addc_co_u32_e32 v175, vcc, 0, v17, vcc
	global_load_dwordx2 v[174:175], v[174:175], off
	v_add_co_u32_e32 v176, vcc, s87, v16
	s_nop 1
	v_addc_co_u32_e32 v177, vcc, 0, v17, vcc
	global_load_dwordx2 v[176:177], v[176:177], off
	v_readlane_b32 s10, v19, 2
	s_waitcnt vmcnt(28)
	s_nop 0
	v_pk_fma_f32 v[20:21], v[120:121], s[10:11], v[20:21] op_sel_hi:[1,0,1]
	v_readlane_b32 s10, v19, 3
	s_waitcnt vmcnt(27)
	s_nop 0
	v_pk_fma_f32 v[20:21], v[122:123], s[10:11], v[20:21] op_sel_hi:[1,0,1]
	v_readlane_b32 s10, v19, 4
	s_waitcnt vmcnt(26)
	s_nop 0
	v_pk_fma_f32 v[20:21], v[124:125], s[10:11], v[20:21] op_sel_hi:[1,0,1]
	v_readlane_b32 s10, v19, 5
	s_waitcnt vmcnt(25)
	s_nop 0
	v_pk_fma_f32 v[20:21], v[126:127], s[10:11], v[20:21] op_sel_hi:[1,0,1]
	v_readlane_b32 s10, v19, 6
	s_waitcnt vmcnt(24)
	s_nop 0
	v_pk_fma_f32 v[20:21], v[128:129], s[10:11], v[20:21] op_sel_hi:[1,0,1]
	v_readlane_b32 s10, v19, 7
	s_waitcnt vmcnt(23)
	s_nop 0
	v_pk_fma_f32 v[20:21], v[130:131], s[10:11], v[20:21] op_sel_hi:[1,0,1]
	v_readlane_b32 s10, v19, 8
	s_waitcnt vmcnt(22)
	s_nop 0
	v_pk_fma_f32 v[20:21], v[132:133], s[10:11], v[20:21] op_sel_hi:[1,0,1]
	v_readlane_b32 s10, v19, 9
	s_waitcnt vmcnt(21)
	s_nop 0
	v_pk_fma_f32 v[20:21], v[134:135], s[10:11], v[20:21] op_sel_hi:[1,0,1]
	v_readlane_b32 s10, v19, 10
	s_waitcnt vmcnt(20)
	s_nop 0
	v_pk_fma_f32 v[20:21], v[136:137], s[10:11], v[20:21] op_sel_hi:[1,0,1]
	v_readlane_b32 s10, v19, 11
	s_waitcnt vmcnt(19)
	s_nop 0
	v_pk_fma_f32 v[20:21], v[138:139], s[10:11], v[20:21] op_sel_hi:[1,0,1]
	v_readlane_b32 s10, v19, 12
	s_waitcnt vmcnt(18)
	s_nop 0
	v_pk_fma_f32 v[20:21], v[140:141], s[10:11], v[20:21] op_sel_hi:[1,0,1]
	v_readlane_b32 s10, v19, 13
	s_waitcnt vmcnt(17)
	s_nop 0
	v_pk_fma_f32 v[20:21], v[142:143], s[10:11], v[20:21] op_sel_hi:[1,0,1]
	v_readlane_b32 s10, v19, 14
	s_waitcnt vmcnt(16)
	s_nop 0
	v_pk_fma_f32 v[20:21], v[144:145], s[10:11], v[20:21] op_sel_hi:[1,0,1]
	v_readlane_b32 s10, v19, 15
	s_waitcnt vmcnt(15)
	s_nop 0
	v_pk_fma_f32 v[20:21], v[146:147], s[10:11], v[20:21] op_sel_hi:[1,0,1]
	v_readlane_b32 s10, v19, 16
	s_waitcnt vmcnt(14)
	s_nop 0
	v_pk_fma_f32 v[20:21], v[148:149], s[10:11], v[20:21] op_sel_hi:[1,0,1]
	v_readlane_b32 s10, v19, 17
	s_waitcnt vmcnt(13)
	s_nop 0
	v_pk_fma_f32 v[20:21], v[150:151], s[10:11], v[20:21] op_sel_hi:[1,0,1]
	v_readlane_b32 s10, v19, 18
	s_waitcnt vmcnt(12)
	s_nop 0
	v_pk_fma_f32 v[20:21], v[152:153], s[10:11], v[20:21] op_sel_hi:[1,0,1]
	v_readlane_b32 s10, v19, 19
	s_waitcnt vmcnt(11)
	s_nop 0
	v_pk_fma_f32 v[20:21], v[154:155], s[10:11], v[20:21] op_sel_hi:[1,0,1]
	v_readlane_b32 s10, v19, 20
	s_waitcnt vmcnt(10)
	s_nop 0
	v_pk_fma_f32 v[20:21], v[156:157], s[10:11], v[20:21] op_sel_hi:[1,0,1]
	v_readlane_b32 s10, v19, 21
	s_waitcnt vmcnt(9)
	s_nop 0
	v_pk_fma_f32 v[20:21], v[158:159], s[10:11], v[20:21] op_sel_hi:[1,0,1]
	v_readlane_b32 s10, v19, 22
	s_waitcnt vmcnt(8)
	s_nop 0
	v_pk_fma_f32 v[20:21], v[160:161], s[10:11], v[20:21] op_sel_hi:[1,0,1]
	v_readlane_b32 s10, v19, 23
	s_waitcnt vmcnt(7)
	s_nop 0
	v_pk_fma_f32 v[20:21], v[162:163], s[10:11], v[20:21] op_sel_hi:[1,0,1]
	v_readlane_b32 s10, v19, 24
	s_waitcnt vmcnt(6)
	s_nop 0
	v_pk_fma_f32 v[20:21], v[164:165], s[10:11], v[20:21] op_sel_hi:[1,0,1]
	v_readlane_b32 s10, v19, 25
	s_waitcnt vmcnt(5)
	s_nop 0
	v_pk_fma_f32 v[20:21], v[166:167], s[10:11], v[20:21] op_sel_hi:[1,0,1]
	v_readlane_b32 s10, v19, 26
	s_waitcnt vmcnt(4)
	s_nop 0
	v_pk_fma_f32 v[20:21], v[168:169], s[10:11], v[20:21] op_sel_hi:[1,0,1]
	v_readlane_b32 s10, v19, 27
	s_waitcnt vmcnt(3)
	s_nop 0
	v_pk_fma_f32 v[20:21], v[170:171], s[10:11], v[20:21] op_sel_hi:[1,0,1]
	v_readlane_b32 s10, v19, 28
	s_waitcnt vmcnt(2)
	s_nop 0
	v_pk_fma_f32 v[20:21], v[172:173], s[10:11], v[20:21] op_sel_hi:[1,0,1]
	v_readlane_b32 s10, v19, 29
	s_waitcnt vmcnt(1)
	s_nop 0
	v_pk_fma_f32 v[20:21], v[174:175], s[10:11], v[20:21] op_sel_hi:[1,0,1]
	v_readlane_b32 s10, v19, 30
	s_waitcnt vmcnt(0)
	s_nop 0
	v_pk_fma_f32 v[20:21], v[176:177], s[10:11], v[20:21] op_sel_hi:[1,0,1]
	v_add_co_u32_e32 v22, vcc, s20, v16
	s_mov_b32 s20, 0x40000
	s_nop 0
	v_addc_co_u32_e32 v23, vcc, 0, v17, vcc
	global_load_dwordx2 v[22:23], v[22:23], off
	v_add_co_u32_e32 v16, vcc, s20, v16
	v_readlane_b32 s10, v19, 31
	s_nop 0
	v_addc_co_u32_e32 v17, vcc, 0, v17, vcc
	global_load_dwordx2 v[16:17], v[16:17], off
	v_div_scale_f32 v18, s[20:21], v15, v15, 1.0
	s_add_i32 s20, s93, 0x2000
	s_ashr_i32 s21, s20, 31
	s_lshl_b64 s[22:23], s[20:21], 12
	s_lshl_b64 s[20:21], s[20:21], 11
	s_cmpk_gt_i32 s91, 0x1ff
	s_waitcnt vmcnt(1)
	v_pk_fma_f32 v[20:21], v[22:23], s[10:11], v[20:21] op_sel_hi:[1,0,1]
	v_readlane_b32 s10, v19, 32
	v_rcp_f32_e32 v19, v18
	s_waitcnt vmcnt(0)
	v_pk_fma_f32 v[16:17], v[16:17], s[10:11], v[20:21] op_sel_hi:[1,0,1]
	v_fma_f32 v20, -v18, v19, 1.0
	v_fmac_f32_e32 v19, v20, v19
	v_div_scale_f32 v20, vcc, 1.0, v15, 1.0
	v_mul_f32_e32 v21, v20, v19
	v_fma_f32 v22, -v18, v21, v20
	v_fmac_f32_e32 v21, v22, v19
	v_fma_f32 v18, -v18, v21, v20
	v_div_fmas_f32 v18, v18, v19, v21
	v_div_fixup_f32 v18, v18, v15, 1.0
	v_pk_mul_f32 v[16:17], v[18:19], v[16:17] op_sel_hi:[0,1]
	v_pk_mul_f32 v[16:17], v[56:57], v[16:17]
	s_nop 0
	v_pk_fma_f32 v[12:13], v[14:15], v[12:13], v[16:17] op_sel_hi:[0,1,1] neg_lo:[0,0,1] neg_hi:[0,0,1]
	v_pk_mul_f32 v[14:15], v[12:13], v[12:13]
	s_nop 0
	v_add_f32_e32 v14, v14, v15
	ds_swizzle_b32 v15, v14 offset:swizzle(SWAP,1)
	s_waitcnt lgkmcnt(0)
	v_add_f32_e32 v14, v14, v15
	ds_swizzle_b32 v15, v14 offset:swizzle(SWAP,2)
	s_waitcnt lgkmcnt(0)
	v_add_f32_e32 v14, v14, v15
	ds_swizzle_b32 v15, v14 offset:swizzle(SWAP,4)
	s_waitcnt lgkmcnt(0)
	v_add_f32_e32 v14, v14, v15
	ds_swizzle_b32 v15, v14 offset:swizzle(SWAP,8)
	s_waitcnt lgkmcnt(0)
	v_add_f32_e32 v14, v14, v15
	ds_swizzle_b32 v15, v14 offset:swizzle(SWAP,16)
	s_waitcnt lgkmcnt(0)
	v_add_f32_e32 v14, v14, v15
	v_mov_b32_e32 v15, v14
	s_nop 1
	v_permlane32_swap_b32_e32 v14, v15
	v_add_f32_e32 v14, v14, v15
	v_fmamk_f32 v14, v14, 0x3c000000, v86
	v_cmp_gt_f32_e32 vcc, s89, v14
	v_mul_f32_e32 v15, 0x4b800000, v14
	s_nop 0
	v_cndmask_b32_e32 v14, v14, v15, vcc
	v_rsq_f32_e32 v14, v14
	s_nop 0
	v_mul_f32_e32 v15, 0x45800000, v14
	v_cndmask_b32_e32 v14, v14, v15, vcc
	v_mul_f32_e32 v14, 0x3f4ccccd, v14
	v_pk_mul_f32 v[12:13], v[12:13], v[14:15] op_sel_hi:[1,0]
	v_mov_b32_e32 v15, s21
	v_pk_mul_f32 v[12:13], v[2:3], v[12:13]
	s_nop 0
	v_cvt_pk_bf16_f32 v14, v12, v13
	v_lshl_add_u64 v[12:13], v[10:11], 0, s[22:23]
	global_store_dword v[12:13], v14, off
	v_lshl_or_b32 v14, v6, 1, s20
	v_lshl_add_u64 v[16:17], s[12:13], 0, v[14:15]
	global_load_dword v17, v[16:17], off
	v_lshl_add_u64 v[14:15], s[14:15], 0, v[14:15]
	global_load_dword v15, v[14:15], off
	s_waitcnt vmcnt(1)
	v_lshlrev_b32_e32 v16, 16, v17
	v_and_b32_e32 v17, 0xffff0000, v17
	v_pk_mul_f32 v[18:19], v[16:17], v[16:17]
	s_waitcnt vmcnt(0)
	v_lshlrev_b32_e32 v14, 16, v15
	v_add_f32_e32 v18, v18, v19
	ds_swizzle_b32 v19, v18 offset:swizzle(SWAP,1)
	v_and_b32_e32 v15, 0xffff0000, v15
	s_waitcnt lgkmcnt(0)
	v_add_f32_e32 v18, v18, v19
	ds_swizzle_b32 v19, v18 offset:swizzle(SWAP,2)
	s_waitcnt lgkmcnt(0)
	v_add_f32_e32 v18, v18, v19
	ds_swizzle_b32 v19, v18 offset:swizzle(SWAP,4)
	s_waitcnt lgkmcnt(0)
	v_add_f32_e32 v18, v18, v19
	ds_swizzle_b32 v19, v18 offset:swizzle(SWAP,8)
	s_waitcnt lgkmcnt(0)
	v_add_f32_e32 v18, v18, v19
	ds_swizzle_b32 v19, v18 offset:swizzle(SWAP,16)
	s_waitcnt lgkmcnt(0)
	v_add_f32_e32 v18, v18, v19
	v_mov_b32_e32 v19, v18
	s_nop 1
	v_permlane32_swap_b32_e32 v18, v19
	v_add_f32_e32 v18, v18, v19
	v_fmamk_f32 v18, v18, 0x3c000000, v86
	v_cmp_gt_f32_e32 vcc, s89, v18
	v_mul_f32_e32 v19, 0x4b800000, v18
	s_nop 0
	v_cndmask_b32_e32 v18, v18, v19, vcc
	v_rsq_f32_e32 v18, v18
	s_nop 0
	v_mul_f32_e32 v19, 0x45800000, v18
	v_cndmask_b32_e32 v18, v18, v19, vcc
	v_mul_f32_e32 v19, 0xbfb8aa3b, v14
	v_exp_f32_e32 v19, v19
	s_nop 0
	v_add_f32_e32 v19, 1.0, v19
	v_pk_mul_f32 v[16:17], v[18:19], v[16:17] op_sel_hi:[0,1]
	v_mul_f32_e32 v18, 0xbfb8aa3b, v15
	v_exp_f32_e32 v18, v18
	v_rcp_f32_e32 v20, v19
	v_pk_mul_f32 v[16:17], v[0:1], v[16:17]
	v_add_f32_e32 v18, 1.0, v18
	v_rcp_f32_e32 v21, v18
	s_nop 0
	v_pk_mul_f32 v[14:15], v[20:21], v[14:15]
	s_nop 0
	v_pk_mul_f32 v[14:15], v[14:15], v[16:17]
	s_nop 0
	v_cvt_pk_bf16_f32 v14, v14, v15
	global_store_dword v[12:13], v14, off offset:2048
	s_cbranch_scc1 .LBB0_2137
